# speedup vs baseline: 1.0281x; 1.0084x over previous
; __device__ __forceinline__ int opaque_tid(int wave_s) { int l; asm volatile("v_mbcnt_lo_u32_b32 %0, -1, 0\n\tv_mbcnt_hi_u32_b32 %0, -1, %0" : "=v"(l)); return (wave_s << 6) | l; }
; __device__ __forceinline__ unsigned pk2(float lo, float hi) { return pg8::cvt_pk_bf16(lo, hi); }
; __device__ __forceinline__ void norm_row(const float* src, const float* g, bf16* dst, float* hdst, int lane) {
;     f32x4 v[8]; float ss = 0.f;
; #pragma unroll
;     for (int j = 0; j < 8; ++j) { v[j] = src ? *(const f32x4*)(src + 4 * lane + 256 * j) : (f32x4){0.f, 0.f, 0.f, 0.f}; ss += v[j].x * v[j].x + v[j].y * v[j].y + v[j].z * v[j].z + v[j].w * v[j].w; }
;     ss = wave_sum(ss);
;     const float rstd = rsqrtf(ss * (1.0f / DM) + EPS);
; #pragma unroll
;     for (int j = 0; j < 8; ++j) {
;         const f32x4 gg = *(const f32x4*)(g + 4 * lane + 256 * j);
;         u32x2 w; w.x = pk2(v[j].x * rstd * gg.x, v[j].y * rstd * gg.y); w.y = pk2(v[j].z * rstd * gg.z, v[j].w * rstd * gg.w);
;         *(u32x2*)(dst + 4 * lane + 256 * j) = w;
;         if (hdst) *(f32x4*)(hdst + 4 * lane + 256 * j) = v[j];
;     }
; }
; __device__ __forceinline__ void phase_norm(KA a, const float* g, int vcu, int G, int wave) {
;     const int lane = opaque_tid(wave) & 63;
;     const int gw = vcu * NWAVES + wave, NGW = G * NWAVES;
;     for (int t = gw; t < T_; t += NGW) norm_row((const float*)(a->ws + WS_H) + (size_t)t * DM, g, (bf16*)(a->ws + WS_HN) + (size_t)t * DM, nullptr, lane);
; }
.LBB0_434:
	s_and_b64 vcc, exec, s[0:1]
	s_cbranch_vccz .LBB0_439
	s_lshl_b32 s5, s81, 8
	s_add_i32 s5, s5, s11
	s_sub_i32 s5, s5, s81
	s_add_i32 s20, s5, s81
	s_cmpk_lt_i32 s20, 0x2010
	s_mov_b32 s0, 0x1b800000
	v_mbcnt_lo_u32_b32 v0, -1, 0
	v_mbcnt_hi_u32_b32 v0, -1, v0
	s_cbranch_scc0 .LBB0_438
	v_and_b32_e32 v1, 64, v196
	v_add_u32_e32 v1, 64, v1
	v_xor_b32_e32 v2, 1, v196
	v_cmp_lt_i32_e32 vcc, v2, v1
	s_load_dwordx2 s[18:19], s[36:37], 0x10
	v_readlane_b32 s1, v254, 62
	v_cndmask_b32_e32 v2, v196, v2, vcc
	v_lshlrev_b32_e32 v48, 2, v2
	v_xor_b32_e32 v2, 2, v196
	v_cmp_lt_i32_e32 vcc, v2, v1
	s_lshl_b32 s3, s1, 11
	s_add_i32 s22, s3, 0x800
	v_cndmask_b32_e32 v2, v196, v2, vcc
	v_lshlrev_b32_e32 v49, 2, v2
	v_xor_b32_e32 v2, 4, v196
	v_cmp_lt_i32_e32 vcc, v2, v1
	s_ashr_i32 s23, s22, 31
	s_waitcnt lgkmcnt(0)
	s_lshl_b32 s40, s15, 3
	v_cndmask_b32_e32 v2, v196, v2, vcc
	v_lshlrev_b32_e32 v50, 2, v2
	v_xor_b32_e32 v2, 8, v196
	v_cmp_lt_i32_e32 vcc, v2, v1
	s_lshl_b64 s[22:23], s[22:23], 2
	s_add_u32 s18, s18, s22
	v_cndmask_b32_e32 v2, v196, v2, vcc
	v_lshlrev_b32_e32 v51, 2, v2
	v_xor_b32_e32 v2, 16, v196
	v_cmp_lt_i32_e32 vcc, v2, v1
	s_addc_u32 s19, s19, s23
	s_ashr_i32 s21, s20, 31
	v_cndmask_b32_e32 v2, v196, v2, vcc
	v_lshlrev_b32_e32 v52, 2, v2
	v_xor_b32_e32 v2, 32, v196
	v_cmp_lt_i32_e32 vcc, v2, v1
	s_ashr_i32 s41, s40, 31
	s_lshl_b64 s[42:43], s[40:41], 12
	v_cndmask_b32_e32 v1, v196, v2, vcc
	v_lshlrev_b32_e32 v53, 2, v1
	v_lshlrev_b32_e32 v1, 4, v0
	v_and_b32_e32 v148, 0x3f0, v1
	v_lshl_add_u64 v[32:33], s[18:19], 0, v[148:149]
	s_mov_b64 s[18:19], 0x1000
	v_lshl_add_u64 v[34:35], v[32:33], 0, s[18:19]
	s_mov_b64 s[18:19], 0x1400
	v_lshl_add_u64 v[36:37], v[32:33], 0, s[18:19]
	s_mov_b64 s[18:19], 0x1800
	v_lshl_add_u64 v[38:39], v[32:33], 0, s[18:19]
	s_mov_b64 s[18:19], 0x1c00
	v_lshl_add_u64 v[40:41], v[32:33], 0, s[18:19]
	s_lshl_b64 s[18:19], s[20:21], 12
	v_and_b32_e32 v0, 63, v0
	v_lshl_or_b32 v42, v0, 3, s18
	v_mov_b32_e32 v43, s19
	s_lshl_b64 s[18:19], s[20:21], 13
	v_lshl_or_b32 v44, v0, 4, s18
	v_mov_b32_e32 v45, s19
	s_lshl_b64 s[44:45], s[40:41], 13
	global_load_dwordx4 v[64:67], v[32:33], off
	global_load_dwordx4 v[68:71], v[32:33], off offset:1024
	global_load_dwordx4 v[72:75], v[32:33], off offset:2048
	global_load_dwordx4 v[76:79], v[32:33], off offset:3072
	global_load_dwordx4 v[80:83], v[34:35], off
	global_load_dwordx4 v[84:87], v[36:37], off
	global_load_dwordx4 v[88:91], v[38:39], off
	global_load_dwordx4 v[92:95], v[40:41], off
; __device__ __forceinline__ unsigned pk2(float lo, float hi) { return pg8::cvt_pk_bf16(lo, hi); }
; __device__ __forceinline__ void norm_row(const float* src, const float* g, bf16* dst, float* hdst, int lane) {
;     f32x4 v[8]; float ss = 0.f;
; #pragma unroll
;     for (int j = 0; j < 8; ++j) { v[j] = src ? *(const f32x4*)(src + 4 * lane + 256 * j) : (f32x4){0.f, 0.f, 0.f, 0.f}; ss += v[j].x * v[j].x + v[j].y * v[j].y + v[j].z * v[j].z + v[j].w * v[j].w; }
;     ss = wave_sum(ss);
;     const float rstd = rsqrtf(ss * (1.0f / DM) + EPS);
; #pragma unroll
;     for (int j = 0; j < 8; ++j) {
;         const f32x4 gg = *(const f32x4*)(g + 4 * lane + 256 * j);
;         u32x2 w; w.x = pk2(v[j].x * rstd * gg.x, v[j].y * rstd * gg.y); w.y = pk2(v[j].z * rstd * gg.z, v[j].w * rstd * gg.w);
;         *(u32x2*)(dst + 4 * lane + 256 * j) = w;
;         if (hdst) *(f32x4*)(hdst + 4 * lane + 256 * j) = v[j];
;     }
; }
.LBB0_437:
	v_lshl_add_u64 v[0:1], s[16:17], 0, v[44:45]
	v_add_co_u32_e32 v2, vcc, 0x17600000, v0
	v_lshl_add_u64 v[60:61], s[16:17], 0, v[42:43]
	s_nop 0
	v_addc_co_u32_e32 v3, vcc, 0, v1, vcc
	global_load_dwordx4 v[28:31], v[2:3], off
	global_load_dwordx4 v[24:27], v[2:3], off offset:1024
	global_load_dwordx4 v[20:23], v[2:3], off offset:2048
	global_load_dwordx4 v[16:19], v[2:3], off offset:3072
	v_add_co_u32_e32 v0, vcc, s26, v0
	s_add_i32 s20, s20, s40
	s_nop 0
	v_addc_co_u32_e32 v1, vcc, 0, v1, vcc
	global_load_dwordx4 v[12:15], v[0:1], off
	global_load_dwordx4 v[8:11], v[0:1], off offset:1024
	global_load_dwordx4 v[96:99], v[0:1], off offset:2048
	global_load_dwordx4 v[100:103], v[0:1], off offset:3072
	v_lshl_add_u64 v[42:43], v[42:43], 0, s[42:43]
	v_lshl_add_u64 v[44:45], v[44:45], 0, s[44:45]
	s_cmpk_gt_i32 s20, 0x200f
	s_waitcnt vmcnt(0)
	v_mul_f32_e32 v4, v29, v29
	v_mul_f32_e32 v5, v25, v25
	v_fmac_f32_e32 v4, v28, v28
	v_fmac_f32_e32 v5, v24, v24
	v_fmac_f32_e32 v4, v30, v30
	v_fmac_f32_e32 v5, v26, v26
	v_fmac_f32_e32 v4, v31, v31
	v_fmac_f32_e32 v5, v27, v27
	v_add_f32_e32 v4, v4, v5
	v_mul_f32_e32 v5, v21, v21
	v_fmac_f32_e32 v5, v20, v20
	v_mul_f32_e32 v2, v17, v17
	v_fmac_f32_e32 v5, v22, v22
	v_fmac_f32_e32 v2, v16, v16
	v_fmac_f32_e32 v5, v23, v23
	v_fmac_f32_e32 v2, v18, v18
	v_add_f32_e32 v4, v4, v5
	v_fmac_f32_e32 v2, v19, v19
	v_add_f32_e32 v6, v4, v2
	v_mov_b32_e32 v4, v13
	v_mov_b32_e32 v5, v9
	v_mov_b32_e32 v2, v12
	v_mov_b32_e32 v3, v8
	v_pk_mul_f32 v[4:5], v[4:5], v[4:5]
	s_nop 0
	v_pk_fma_f32 v[2:3], v[2:3], v[2:3], v[4:5]
	v_mov_b32_e32 v4, v14
	v_mov_b32_e32 v5, v10
	v_pk_fma_f32 v[2:3], v[4:5], v[4:5], v[2:3]
	v_mov_b32_e32 v4, v15
	v_mov_b32_e32 v5, v11
	v_pk_fma_f32 v[2:3], v[4:5], v[4:5], v[2:3]
	s_nop 0
	v_add_f32_e32 v2, v6, v2
	v_add_f32_e32 v56, v2, v3
	v_mov_b32_e32 v4, v96
	v_mov_b32_e32 v5, v97
	v_mov_b32_e32 v6, v98
	v_mov_b32_e32 v7, v99
	s_nop 0
	v_mov_b32_e32 v0, v100
	v_mov_b32_e32 v1, v101
	v_mov_b32_e32 v2, v102
	v_mov_b32_e32 v3, v103
	v_mov_b32_e32 v54, v5
	v_mov_b32_e32 v55, v1
	v_mov_b32_e32 v46, v4
	v_mov_b32_e32 v47, v0
	v_pk_mul_f32 v[54:55], v[54:55], v[54:55]
	s_nop 0
	v_pk_fma_f32 v[46:47], v[46:47], v[46:47], v[54:55]
	v_mov_b32_e32 v54, v6
	v_mov_b32_e32 v55, v2
	v_pk_fma_f32 v[46:47], v[54:55], v[54:55], v[46:47]
	v_mov_b32_e32 v54, v7
	v_mov_b32_e32 v55, v3
	v_pk_fma_f32 v[46:47], v[54:55], v[54:55], v[46:47]
	s_nop 0
	v_add_f32_e32 v46, v56, v46
	v_add_f32_e32 v46, v46, v47
	ds_bpermute_b32 v47, v48, v46
	s_waitcnt lgkmcnt(0)
	v_add_f32_e32 v46, v46, v47
	ds_bpermute_b32 v47, v49, v46
	s_waitcnt lgkmcnt(0)
	v_add_f32_e32 v46, v46, v47
	ds_bpermute_b32 v47, v50, v46
	s_waitcnt lgkmcnt(0)
	v_add_f32_e32 v46, v46, v47
	ds_bpermute_b32 v47, v51, v46
	s_waitcnt lgkmcnt(0)
	v_add_f32_e32 v46, v46, v47
	ds_bpermute_b32 v47, v52, v46
	s_waitcnt lgkmcnt(0)
	v_add_f32_e32 v46, v46, v47
	ds_bpermute_b32 v47, v53, v46
	s_waitcnt lgkmcnt(0)
	v_add_f32_e32 v46, v46, v47
	v_fmamk_f32 v46, v46, 0x3a000000, v154
	v_cmp_gt_f32_e32 vcc, s54, v46
	v_mul_f32_e32 v47, 0x4b800000, v46
	s_nop 0
	v_cndmask_b32_e32 v46, v46, v47, vcc
	v_rsq_f32_e32 v46, v46
	s_nop 0
	v_mul_f32_e32 v47, 0x45800000, v46
	v_cndmask_b32_e32 v54, v46, v47, vcc
	v_mul_f32_e32 v28, v28, v54
	v_mul_f32_e32 v29, v29, v54
	v_mul_f32_e32 v24, v24, v54
	v_mul_f32_e32 v25, v25, v54
	v_mul_f32_e32 v20, v20, v54
	v_mul_f32_e32 v21, v21, v54
	v_mul_f32_e32 v16, v16, v54
	v_mul_f32_e32 v17, v17, v54
	v_mul_f32_e32 v12, v12, v54
	v_mul_f32_e32 v13, v13, v54
	v_mul_f32_e32 v8, v8, v54
	v_mul_f32_e32 v9, v9, v54
	v_mul_f32_e32 v4, v4, v54
	v_mul_f32_e32 v5, v5, v54
	v_mul_f32_e32 v0, v0, v54
	v_mul_f32_e32 v1, v1, v54
	v_mul_f32_e32 v28, v64, v28
	v_mul_f32_e32 v29, v65, v29
	v_cvt_pk_bf16_f32 v46, v28, v29
	v_mul_f32_e32 v28, v30, v54
	v_mul_f32_e32 v28, v66, v28
	v_mul_f32_e32 v29, v31, v54
	v_mul_f32_e32 v29, v67, v29
	v_cvt_pk_bf16_f32 v47, v28, v29
	v_add_co_u32_e32 v28, vcc, s0, v60
	s_nop 1
	v_addc_co_u32_e32 v29, vcc, 0, v61, vcc
	global_store_dwordx2 v[28:29], v[46:47], off
	v_mul_f32_e32 v24, v68, v24
	v_mul_f32_e32 v25, v69, v25
	v_cvt_pk_bf16_f32 v24, v24, v25
	v_mul_f32_e32 v25, v26, v54
	v_mul_f32_e32 v25, v70, v25
	v_mul_f32_e32 v26, v27, v54
	v_mul_f32_e32 v26, v71, v26
	v_cvt_pk_bf16_f32 v25, v25, v26
	global_store_dwordx2 v[28:29], v[24:25], off offset:512
	v_mul_f32_e32 v20, v72, v20
	v_mul_f32_e32 v21, v73, v21
	v_cvt_pk_bf16_f32 v20, v20, v21
	v_mul_f32_e32 v21, v22, v54
	v_mul_f32_e32 v21, v74, v21
	v_mul_f32_e32 v22, v23, v54
	v_mul_f32_e32 v22, v75, v22
	v_cvt_pk_bf16_f32 v21, v21, v22
	global_store_dwordx2 v[28:29], v[20:21], off offset:1024
	v_mul_f32_e32 v16, v16, v76
	v_mul_f32_e32 v17, v17, v77
	v_cvt_pk_bf16_f32 v16, v16, v17
	v_mul_f32_e32 v17, v18, v54
	v_mul_f32_e32 v17, v17, v78
	v_mul_f32_e32 v18, v19, v54
	v_mul_f32_e32 v18, v18, v79
	v_cvt_pk_bf16_f32 v17, v17, v18
	global_store_dwordx2 v[28:29], v[16:17], off offset:1536
	v_mul_f32_e32 v12, v12, v80
	v_mul_f32_e32 v13, v13, v81
	v_cvt_pk_bf16_f32 v12, v12, v13
	v_mul_f32_e32 v13, v14, v54
	v_mul_f32_e32 v13, v13, v82
	v_mul_f32_e32 v14, v15, v54
	v_mul_f32_e32 v14, v14, v83
	v_cvt_pk_bf16_f32 v13, v13, v14
	global_store_dwordx2 v[28:29], v[12:13], off offset:2048
	v_mul_f32_e32 v8, v8, v84
	v_mul_f32_e32 v9, v9, v85
	v_cvt_pk_bf16_f32 v8, v8, v9
	v_mul_f32_e32 v9, v10, v54
	v_mul_f32_e32 v9, v9, v86
	v_mul_f32_e32 v10, v11, v54
	v_mul_f32_e32 v10, v10, v87
	v_cvt_pk_bf16_f32 v9, v9, v10
	global_store_dwordx2 v[28:29], v[8:9], off offset:2560
	v_mul_f32_e32 v4, v4, v88
	v_mul_f32_e32 v5, v5, v89
	v_cvt_pk_bf16_f32 v4, v4, v5
	v_mul_f32_e32 v5, v6, v54
	v_mul_f32_e32 v5, v5, v90
	v_mul_f32_e32 v6, v7, v54
	v_mul_f32_e32 v6, v6, v91
	v_cvt_pk_bf16_f32 v5, v5, v6
	global_store_dwordx2 v[28:29], v[4:5], off offset:3072
	v_mul_f32_e32 v0, v0, v92
	v_mul_f32_e32 v1, v1, v93
	v_cvt_pk_bf16_f32 v0, v0, v1
	v_mul_f32_e32 v1, v2, v54
	v_mul_f32_e32 v1, v1, v94
	v_mul_f32_e32 v2, v3, v54
	v_mul_f32_e32 v2, v2, v95
	v_cvt_pk_bf16_f32 v1, v1, v2
	global_store_dwordx2 v[28:29], v[0:1], off offset:3584
	s_cbranch_scc0 .LBB0_437

; __device__ __forceinline__ unsigned pk2(float lo, float hi) { return pg8::cvt_pk_bf16(lo, hi); }
; __device__ __forceinline__ void norm_row(const float* src, const float* g, bf16* dst, float* hdst, int lane) {
;     f32x4 v[8]; float ss = 0.f;
; #pragma unroll
;     for (int j = 0; j < 8; ++j) { v[j] = src ? *(const f32x4*)(src + 4 * lane + 256 * j) : (f32x4){0.f, 0.f, 0.f, 0.f}; ss += v[j].x * v[j].x + v[j].y * v[j].y + v[j].z * v[j].z + v[j].w * v[j].w; }
;     ss = wave_sum(ss);
;     const float rstd = rsqrtf(ss * (1.0f / DM) + EPS);
; #pragma unroll
;     for (int j = 0; j < 8; ++j) {
;         const f32x4 gg = *(const f32x4*)(g + 4 * lane + 256 * j);
;         u32x2 w; w.x = pk2(v[j].x * rstd * gg.x, v[j].y * rstd * gg.y); w.y = pk2(v[j].z * rstd * gg.z, v[j].w * rstd * gg.w);
;         *(u32x2*)(dst + 4 * lane + 256 * j) = w;
;         if (hdst) *(f32x4*)(hdst + 4 * lane + 256 * j) = v[j];
;     }
; }
; __device__ __forceinline__ void phase_prologue(KA a, LAS unsigned char* lds, int vcu, int G, int wave) {
;     ...
;     for (int t = gw; t < TP; t += NGW) {
;         const float* src = t < NMETA ? a->in[I_META] + (size_t)t * DM : (t < T_ ? a->in[I_X] + (size_t)(t - NMETA) * DM : nullptr);
;         norm_row(src, a->in[I_NMG], (bf16*)(ws + WS_HN) + (size_t)t * DM, (float*)(ws + WS_H) + (size_t)t * DM, lane);
;     }
.LBB0_598:
	s_cmpk_gt_i32 s18, 0x20ff
	s_mov_b32 s26, 0x17601000
	s_mov_b32 s54, 0x800000
	s_cbranch_scc1 .LBB0_622
	v_and_b32_e32 v1, 64, v196
	v_add_u32_e32 v1, 64, v1
	v_xor_b32_e32 v3, 1, v196
	v_cmp_lt_i32_e32 vcc, v3, v1
	s_load_dwordx2 s[22:23], s[36:37], 0x10
	v_lshlrev_b32_e32 v148, 4, v2
	v_cndmask_b32_e32 v3, v196, v3, vcc
	v_lshlrev_b32_e32 v52, 2, v3
	v_xor_b32_e32 v3, 2, v196
	v_cmp_lt_i32_e32 vcc, v3, v1
	s_waitcnt lgkmcnt(0)
	v_lshl_add_u64 v[32:33], s[22:23], 0, v[148:149]
	s_mov_b64 s[0:1], 0x1000
	v_cndmask_b32_e32 v3, v196, v3, vcc
	v_lshlrev_b32_e32 v53, 2, v3
	v_xor_b32_e32 v3, 4, v196
	v_cmp_lt_i32_e32 vcc, v3, v1
	v_lshl_add_u64 v[34:35], v[32:33], 0, s[0:1]
	s_mov_b64 s[0:1], 0x1400
	v_cndmask_b32_e32 v3, v196, v3, vcc
	v_lshlrev_b32_e32 v54, 2, v3
	v_xor_b32_e32 v3, 8, v196
	v_cmp_lt_i32_e32 vcc, v3, v1
	v_lshl_add_u64 v[36:37], v[32:33], 0, s[0:1]
	s_mov_b64 s[0:1], 0x1800
	v_cndmask_b32_e32 v3, v196, v3, vcc
	v_lshlrev_b32_e32 v55, 2, v3
	v_xor_b32_e32 v3, 16, v196
	v_cmp_lt_i32_e32 vcc, v3, v1
	s_ashr_i32 s19, s18, 31
	v_lshl_add_u64 v[38:39], v[32:33], 0, s[0:1]
	v_cndmask_b32_e32 v3, v196, v3, vcc
	v_lshlrev_b32_e32 v56, 2, v3
	v_xor_b32_e32 v3, 32, v196
	v_cmp_lt_i32_e32 vcc, v3, v1
	s_mov_b64 s[0:1], 0x1c00
	s_lshl_b64 s[42:43], s[18:19], 13
	v_cndmask_b32_e32 v1, v196, v3, vcc
	s_ashr_i32 s21, s20, 31
	s_lshl_b64 s[22:23], s[18:19], 12
	v_lshlrev_b32_e32 v57, 2, v1
	v_lshl_add_u64 v[40:41], v[32:33], 0, s[0:1]
	s_lshl_b64 s[44:45], s[20:21], 13
	v_lshl_or_b32 v42, v2, 4, s42
	v_mov_b32_e32 v43, s43
	v_lshl_or_b32 v44, v2, 3, s22
	v_mov_b32_e32 v45, s23
	s_lshl_b64 s[46:47], s[20:21], 12
	v_lshlrev_b32_e32 v148, 2, v0
	s_mov_b32 s0, 0x1b800000
	global_load_dwordx4 v[64:67], v[32:33], off
	global_load_dwordx4 v[68:71], v[32:33], off offset:1024
	global_load_dwordx4 v[72:75], v[32:33], off offset:2048
	global_load_dwordx4 v[76:79], v[32:33], off offset:3072
	global_load_dwordx4 v[80:83], v[34:35], off
	global_load_dwordx4 v[84:87], v[36:37], off
	global_load_dwordx4 v[88:91], v[38:39], off
	global_load_dwordx4 v[92:95], v[40:41], off
	s_branch .LBB0_601
; __device__ __forceinline__ unsigned pk2(float lo, float hi) { return pg8::cvt_pk_bf16(lo, hi); }
; __device__ __forceinline__ void norm_row(const float* src, const float* g, bf16* dst, float* hdst, int lane) {
;     f32x4 v[8]; float ss = 0.f;
; #pragma unroll
;     for (int j = 0; j < 8; ++j) { v[j] = src ? *(const f32x4*)(src + 4 * lane + 256 * j) : (f32x4){0.f, 0.f, 0.f, 0.f}; ss += v[j].x * v[j].x + v[j].y * v[j].y + v[j].z * v[j].z + v[j].w * v[j].w; }
;     ss = wave_sum(ss);
;     const float rstd = rsqrtf(ss * (1.0f / DM) + EPS);
; #pragma unroll
;     for (int j = 0; j < 8; ++j) {
;         const f32x4 gg = *(const f32x4*)(g + 4 * lane + 256 * j);
;         u32x2 w; w.x = pk2(v[j].x * rstd * gg.x, v[j].y * rstd * gg.y); w.y = pk2(v[j].z * rstd * gg.z, v[j].w * rstd * gg.w);
;         *(u32x2*)(dst + 4 * lane + 256 * j) = w;
;         if (hdst) *(f32x4*)(hdst + 4 * lane + 256 * j) = v[j];
;     }
; }
.LBB0_600:
	v_mul_f32_e32 v46, v29, v29
	v_mul_f32_e32 v47, v25, v25
	v_fmac_f32_e32 v46, v28, v28
	v_fmac_f32_e32 v47, v24, v24
	v_fmac_f32_e32 v46, v30, v30
	v_fmac_f32_e32 v47, v26, v26
	v_fmac_f32_e32 v46, v31, v31
	v_fmac_f32_e32 v47, v27, v27
	v_add_f32_e32 v46, v46, v47
	v_mul_f32_e32 v47, v21, v21
	v_fmac_f32_e32 v47, v20, v20
	v_fmac_f32_e32 v47, v22, v22
	v_fmac_f32_e32 v47, v23, v23
	v_add_f32_e32 v46, v46, v47
	s_waitcnt vmcnt(0)
	v_mul_f32_e32 v47, v13, v13
	v_fmac_f32_e32 v47, v12, v12
	v_fmac_f32_e32 v47, v14, v14
	v_fmac_f32_e32 v47, v15, v15
	v_add_f32_e32 v46, v46, v47
	v_mul_f32_e32 v47, v17, v17
	v_fmac_f32_e32 v47, v16, v16
	v_fmac_f32_e32 v47, v18, v18
	v_fmac_f32_e32 v47, v19, v19
	v_add_f32_e32 v46, v46, v47
	v_mul_f32_e32 v47, v5, v5
	v_fmac_f32_e32 v47, v4, v4
	v_fmac_f32_e32 v47, v6, v6
	v_fmac_f32_e32 v47, v7, v7
	v_add_f32_e32 v46, v46, v47
	v_mul_f32_e32 v47, v9, v9
	v_fmac_f32_e32 v47, v8, v8
	v_fmac_f32_e32 v47, v10, v10
	v_fmac_f32_e32 v47, v11, v11
	v_pk_mul_f32 v[48:49], v[0:1], v[0:1]
	v_add_f32_e32 v50, v46, v47
	v_pk_mul_f32 v[46:47], v[2:3], v[2:3]
	v_add_f32_e32 v48, v48, v49
	v_add_f32_e32 v46, v46, v48
	v_add_f32_e32 v46, v47, v46
	v_add_f32_e32 v46, v50, v46
	ds_bpermute_b32 v47, v52, v46
	v_lshl_add_u64 v[48:49], s[16:17], 0, v[44:45]
	s_mov_b32 s5, 0x17600000
	s_add_i32 s18, s18, s20
	s_add_u32 s42, s42, s44
	s_waitcnt lgkmcnt(0)
	v_add_f32_e32 v46, v46, v47
	ds_bpermute_b32 v47, v53, v46
	s_addc_u32 s43, s43, s45
	v_lshl_add_u64 v[44:45], v[44:45], 0, s[46:47]
	s_cmpk_gt_i32 s18, 0x20ff
	s_waitcnt lgkmcnt(0)
	v_add_f32_e32 v46, v46, v47
	ds_bpermute_b32 v47, v54, v46
	s_waitcnt lgkmcnt(0)
	v_add_f32_e32 v46, v46, v47
	ds_bpermute_b32 v47, v55, v46
	s_waitcnt lgkmcnt(0)
	v_add_f32_e32 v46, v46, v47
	ds_bpermute_b32 v47, v56, v46
	s_waitcnt lgkmcnt(0)
	v_add_f32_e32 v46, v46, v47
	ds_bpermute_b32 v47, v57, v46
	s_waitcnt lgkmcnt(0)
	v_add_f32_e32 v46, v46, v47
	v_fmamk_f32 v46, v46, 0x3a000000, v154
	v_cmp_gt_f32_e32 vcc, s54, v46
	v_mul_f32_e32 v47, 0x4b800000, v46
	s_nop 0
	v_cndmask_b32_e32 v46, v46, v47, vcc
	v_rsq_f32_e32 v46, v46
	s_nop 0
	v_mul_f32_e32 v47, 0x45800000, v46
	v_cndmask_b32_e32 v58, v46, v47, vcc
	v_mul_f32_e32 v50, v28, v58
	v_mul_f32_e32 v51, v29, v58
	s_waitcnt vmcnt(0)
	v_mul_f32_e32 v50, v64, v50
	v_mul_f32_e32 v51, v65, v51
	v_cvt_pk_bf16_f32 v50, v50, v51
	v_mul_f32_e32 v51, v30, v58
	v_add_co_u32_e32 v48, vcc, s0, v48
	v_lshl_add_u64 v[46:47], s[16:17], 0, v[42:43]
	v_mul_f32_e32 v51, v66, v51
	v_mul_f32_e32 v59, v31, v58
	v_addc_co_u32_e32 v49, vcc, 0, v49, vcc
	v_mul_f32_e32 v59, v67, v59
	v_cvt_pk_bf16_f32 v51, v51, v59
	global_store_dwordx2 v[48:49], v[50:51], off
	v_add_co_u32_e32 v50, vcc, s5, v46
	v_mul_f32_e32 v59, v24, v58
	s_nop 0
	v_addc_co_u32_e32 v51, vcc, 0, v47, vcc
	v_add_co_u32_e32 v46, vcc, s26, v46
	v_lshl_add_u64 v[42:43], v[42:43], 0, s[44:45]
	s_nop 0
	v_addc_co_u32_e32 v47, vcc, 0, v47, vcc
	global_store_dwordx4 v[46:47], v[28:31], off offset:-4096
	s_nop 1
	v_mul_f32_e32 v28, v68, v59
	v_mul_f32_e32 v59, v25, v58
	v_mul_f32_e32 v29, v69, v59
	v_cvt_pk_bf16_f32 v28, v28, v29
	v_mul_f32_e32 v29, v26, v58
	v_mul_f32_e32 v29, v70, v29
	v_mul_f32_e32 v30, v27, v58
	v_mul_f32_e32 v30, v71, v30
	v_cvt_pk_bf16_f32 v29, v29, v30
	global_store_dwordx2 v[48:49], v[28:29], off offset:512
	global_store_dwordx4 v[50:51], v[24:27], off offset:1024
	s_nop 1
	v_mul_f32_e32 v28, v20, v58
	v_mul_f32_e32 v24, v72, v28
	v_mul_f32_e32 v28, v21, v58
	v_mul_f32_e32 v25, v73, v28
	v_cvt_pk_bf16_f32 v24, v24, v25
	v_mul_f32_e32 v25, v22, v58
	v_mul_f32_e32 v25, v74, v25
	v_mul_f32_e32 v26, v23, v58
	v_mul_f32_e32 v26, v75, v26
	v_cvt_pk_bf16_f32 v25, v25, v26
	global_store_dwordx2 v[48:49], v[24:25], off offset:1024
	global_store_dwordx4 v[50:51], v[20:23], off offset:2048
	s_nop 1
	v_mul_f32_e32 v24, v12, v58
	v_mul_f32_e32 v20, v24, v76
	v_mul_f32_e32 v24, v13, v58
	v_mul_f32_e32 v21, v24, v77
	v_cvt_pk_bf16_f32 v20, v20, v21
	v_mul_f32_e32 v21, v14, v58
	v_mul_f32_e32 v21, v21, v78
	v_mul_f32_e32 v22, v15, v58
	v_mul_f32_e32 v22, v22, v79
	v_cvt_pk_bf16_f32 v21, v21, v22
	global_store_dwordx2 v[48:49], v[20:21], off offset:1536
	global_store_dwordx4 v[50:51], v[12:15], off offset:3072
	s_nop 1
	v_mul_f32_e32 v20, v16, v58
	v_mul_f32_e32 v12, v20, v80
	v_mul_f32_e32 v20, v17, v58
	v_mul_f32_e32 v13, v20, v81
	v_cvt_pk_bf16_f32 v12, v12, v13
	v_mul_f32_e32 v13, v18, v58
	v_mul_f32_e32 v13, v13, v82
	v_mul_f32_e32 v14, v19, v58
	v_mul_f32_e32 v14, v14, v83
	v_cvt_pk_bf16_f32 v13, v13, v14
	global_store_dwordx2 v[48:49], v[12:13], off offset:2048
	global_store_dwordx4 v[46:47], v[16:19], off
	s_nop 1
	s_nop 0
	v_mul_f32_e32 v16, v4, v58
	v_mul_f32_e32 v12, v16, v84
	v_mul_f32_e32 v16, v5, v58
	v_mul_f32_e32 v13, v16, v85
	v_cvt_pk_bf16_f32 v12, v12, v13
	v_mul_f32_e32 v13, v6, v58
	v_mul_f32_e32 v13, v13, v86
	v_mul_f32_e32 v14, v7, v58
	v_mul_f32_e32 v14, v14, v87
	v_cvt_pk_bf16_f32 v13, v13, v14
	global_store_dwordx2 v[48:49], v[12:13], off offset:2560
	global_store_dwordx4 v[46:47], v[4:7], off offset:1024
	s_nop 1
	v_mul_f32_e32 v12, v8, v58
	v_mul_f32_e32 v4, v12, v88
	v_mul_f32_e32 v12, v9, v58
	v_mul_f32_e32 v5, v12, v89
	v_cvt_pk_bf16_f32 v4, v4, v5
	v_mul_f32_e32 v5, v10, v58
	v_mul_f32_e32 v5, v5, v90
	v_mul_f32_e32 v6, v11, v58
	v_mul_f32_e32 v6, v6, v91
	v_cvt_pk_bf16_f32 v5, v5, v6
	global_store_dwordx2 v[48:49], v[4:5], off offset:3072
	global_store_dwordx4 v[46:47], v[8:11], off offset:2048
	s_nop 1
	s_nop 0
	v_mul_f32_e32 v8, v0, v58
	v_mul_f32_e32 v4, v8, v92
	v_mul_f32_e32 v8, v1, v58
	v_mul_f32_e32 v5, v8, v93
	v_cvt_pk_bf16_f32 v4, v4, v5
	v_mul_f32_e32 v5, v2, v58
	v_mul_f32_e32 v5, v5, v94
	v_mul_f32_e32 v6, v3, v58
	v_mul_f32_e32 v6, v6, v95
	v_cvt_pk_bf16_f32 v5, v5, v6
	global_store_dwordx2 v[48:49], v[4:5], off offset:3584
	global_store_dwordx4 v[46:47], v[0:3], off offset:3072
	s_nop 1
	s_cbranch_scc1 .LBB0_622

; __device__ __forceinline__ unsigned xb_ld(unsigned* p)              { return __hip_atomic_load(p, __ATOMIC_RELAXED, __HIP_MEMORY_SCOPE_AGENT); }
; __device__ __forceinline__ void xcd_barrier_complete(unsigned* bar, unsigned x, unsigned& nloc, unsigned& nx) {
;     const unsigned G = gridDim.x * gridDim.y * gridDim.z;
;     unsigned sum, cnt, mine, sp = 0u;
;     for (;;) {
;         sum = 0u; cnt = 0u; mine = 0u;
; #pragma unroll
;         for (unsigned j = 0; j < 16; ++j) { const unsigned c = xb_ld(&bar[XB_XCNT(j)]); sum += c; cnt += (c > 0u) ? 1u : 0u; mine = (j == x) ? c : mine; }
;         if (sum == G) break;
;         __builtin_amdgcn_s_sleep(1);
;         if ((++sp & 255u) == 0u) { if (xb_ld(&bar[XB_TMO])) break; if (sp > XB_SPIN_CAP) { atomicAdd(&bar[XB_TMO], 1u); break; } }
;     }
;     nloc = mine > 0u ? mine : 1u; nx = cnt > 0u ? cnt : 1u;
; }
.LBB0_641:
	v_readlane_b32 s0, v253, 32
	v_readlane_b32 s1, v253, 33
	s_mov_b64 s[16:17], -1
	s_mov_b64 s[18:19], -1
	s_nop 4
	global_load_dword v0, v149, s[0:1] sc1
	v_readlane_b32 s0, v253, 34
	v_readlane_b32 s1, v253, 35
	s_nop 4
	global_load_dword v1, v149, s[0:1] sc1
	v_readlane_b32 s0, v253, 36
	v_readlane_b32 s1, v253, 37
	s_nop 4
	global_load_dword v2, v149, s[0:1] sc1
	v_readlane_b32 s0, v253, 38
	v_readlane_b32 s1, v253, 39
	s_nop 4
	global_load_dword v3, v149, s[0:1] sc1
	v_readlane_b32 s0, v253, 40
	v_readlane_b32 s1, v253, 41
	s_nop 4
	global_load_dword v4, v149, s[0:1] sc1
	v_readlane_b32 s0, v253, 42
	v_readlane_b32 s1, v253, 43
	s_nop 4
	global_load_dword v5, v149, s[0:1] sc1
	v_readlane_b32 s0, v253, 44
	v_readlane_b32 s1, v253, 45
	s_nop 4
	global_load_dword v6, v149, s[0:1] sc1
	v_readlane_b32 s0, v253, 46
	v_readlane_b32 s1, v253, 47
	s_nop 4
	global_load_dword v7, v149, s[0:1] sc1
	v_readlane_b32 s0, v253, 48
	v_readlane_b32 s1, v253, 49
	s_nop 4
	global_load_dword v8, v149, s[0:1] sc1
	v_readlane_b32 s0, v253, 50
	v_readlane_b32 s1, v253, 51
	s_nop 4
	global_load_dword v9, v149, s[0:1] sc1
	v_readlane_b32 s0, v253, 52
	v_readlane_b32 s1, v253, 53
	s_nop 4
	global_load_dword v10, v149, s[0:1] sc1
	v_readlane_b32 s0, v253, 54
	v_readlane_b32 s1, v253, 55
	s_nop 4
	global_load_dword v11, v149, s[0:1] sc1
	v_readlane_b32 s0, v253, 56
	v_readlane_b32 s1, v253, 57
	s_nop 4
	global_load_dword v12, v149, s[0:1] sc1
	v_readlane_b32 s0, v253, 58
	v_readlane_b32 s1, v253, 59
	s_nop 4
	global_load_dword v13, v149, s[0:1] sc1
	v_readlane_b32 s0, v253, 60
	v_readlane_b32 s1, v253, 61
	s_nop 4
	global_load_dword v14, v149, s[0:1] sc1
	v_readlane_b32 s0, v253, 62
	v_readlane_b32 s1, v253, 63
	s_nop 4
	global_load_dword v15, v149, s[0:1] sc1
	s_waitcnt vmcnt(0)
	v_add_u32_e32 v16, v1, v0
	v_add_u32_e32 v16, v16, v2
	v_add_u32_e32 v16, v16, v3
	v_add_u32_e32 v16, v16, v4
	v_add_u32_e32 v16, v16, v5
	v_add_u32_e32 v16, v16, v6
	v_add_u32_e32 v16, v16, v7
	v_add_u32_e32 v16, v16, v8
	v_add_u32_e32 v16, v16, v9
	v_add_u32_e32 v16, v16, v10
	v_add_u32_e32 v16, v16, v11
	v_add_u32_e32 v16, v16, v12
	v_add_u32_e32 v16, v16, v13
	v_add_u32_e32 v16, v16, v14
	v_add_u32_e32 v16, v16, v15
	v_cmp_eq_u32_e32 vcc, s5, v16
	s_cbranch_vccnz .LBB0_640
	s_and_b32 s3, s7, 0xff
	s_cmp_eq_u32 s3, 0
	s_mov_b64 s[20:21], -1
	s_sleep 1
	s_cbranch_scc1 .LBB0_645
	s_and_b64 vcc, exec, s[20:21]
	s_cbranch_vccz .LBB0_640
